# attention loop: odd half shifted +4 bytes (placement scan)
# speedup vs baseline: 1.0014x; 1.0014x over previous
; #define DMAT(kt, so) do { const unsigned rb_ = (unsigned)ROWBASE(kt); _Pragma("unroll") for (int r = 0; r < 3; ++r) if (wid + 8 * r < 22) \
;         __builtin_amdgcn_global_load_lds((const unsigned*)(dsrc[r] + (size_t)rb_ * dmul[r]), (LAS unsigned*)(lds + (so) + dlds[r]), 16, 0, 0); } while (0)
; __device__ __forceinline__ void attn_unit2(LAS unsigned char* lds, const bf16_t* __restrict__ Q, const bf16_t* __restrict__ KN, const bf16_t* __restrict__ KPE, ...
;     ...
;         if (t + 2 < ntiles) DMAT(t + 2, snn);
.Lat_back_bE:
	v_exp_f32_e32 v80, v80
	v_exp_f32_e32 v81, v81
	v_exp_f32_e32 v82, v82
	v_exp_f32_e32 v83, v83
	v_mfma_f32_32x32x16_bf16 v[112:127], v[220:223], v[154:157], v[112:127]
	ds_read_b128 v[220:223], v224 offset:6816
	v_exp_f32_e32 v84, v84
	v_exp_f32_e32 v85, v85
	v_add_f32_e32 v230, v80, v81
	v_exp_f32_e32 v86, v86
	v_exp_f32_e32 v87, v87
	s_waitcnt lgkmcnt(2)
	v_mfma_f32_32x32x16_bf16 v[96:111], v[212:215], v[150:153], v[96:111]
	v_add_f32_e32 v231, v82, v83
	v_exp_f32_e32 v88, v88
	v_exp_f32_e32 v89, v89
	v_add_f32_e32 v230, v230, v84
	v_add_f32_e32 v231, v231, v85
	v_mfma_f32_32x32x16_bf16 v[112:127], v[212:215], v[158:161], v[112:127]
	v_exp_f32_e32 v90, v90
	v_exp_f32_e32 v91, v91
	v_add_f32_e32 v230, v230, v86
	v_add_f32_e32 v231, v231, v87
	s_waitcnt lgkmcnt(1)
	v_mfma_f32_32x32x16_bf16 v[96:111], v[216:219], v[162:165], v[96:111]
	v_exp_f32_e32 v92, v92
	v_exp_f32_e32 v93, v93
	v_add_f32_e32 v230, v230, v88
	v_add_f32_e32 v231, v231, v89
	v_exp_f32_e32 v94, v94
	v_mfma_f32_32x32x16_bf16 v[112:127], v[216:219], v[170:173], v[112:127]
	v_exp_f32_e32 v95, v95
	v_add_f32_e32 v230, v230, v90
	v_add_f32_e32 v231, v231, v91
	v_add_f32_e32 v230, v230, v92
	v_add_f32_e32 v231, v231, v93
	s_waitcnt lgkmcnt(0)
	v_mfma_f32_32x32x16_bf16 v[96:111], v[220:223], v[166:169], v[96:111]
	v_add_f32_e32 v230, v230, v94
	v_add_f32_e32 v231, v231, v95
	v_add_f32_e32 v230, v230, v231
	v_add_f32_e32 v193, v193, v230
	v_mfma_f32_32x32x16_bf16 v[112:127], v[220:223], v[174:177], v[112:127]
	v_cvt_pk_bf16_f32 v80, v80, v81
	v_cvt_pk_bf16_f32 v81, v82, v83
	v_cvt_pk_bf16_f32 v82, v84, v85
	v_cvt_pk_bf16_f32 v83, v86, v87
	v_cvt_pk_bf16_f32 v84, v88, v89
	v_mfma_f32_32x32x16_bf16 v[112:127], v[240:243], v[248:251], v[112:127]
	v_cvt_pk_bf16_f32 v85, v90, v91
	v_cvt_pk_bf16_f32 v86, v92, v93
	v_cvt_pk_bf16_f32 v87, v94, v95
	s_waitcnt vmcnt(0)
	s_barrier
	s_nop 0
	s_cmpk_gt_u32 s27, 0x81
	s_cbranch_scc1 .Lat_dma_endL
	s_cmp_lt_u32 s27, 2
	s_cselect_b32 s14, s10, s11
	s_add_i32 s14, s14, s24
	s_and_b64 vcc, exec, s[4:5]
	s_cbranch_vccnz .Lat_dmaL_0
	v_mad_u64_u32 v[234:235], s[16:17], v182, s14, v[180:181]
	s_add_i32 m0, s25, s19
	s_nop 0
	global_load_lds_dwordx4 v[234:235], off
